# speedup vs baseline: 1.0053x; 1.0053x over previous
; __device__ __forceinline__ float bf2f(u16 b) { return __uint_as_float(((unsigned)b) << 16); }
; __device__ void final_phase(KP p) {
;   const int tid = tid_v();
;   const int wave = tid >> 6, lane = tid & 63;
;   for (int row = bid_s() * 8 + wave; row < S_; row += gridDim.x * 8) {
;     float ss = (lane < 32) ? p->rowss[(size_t)lane * S_ + row] : 0.f;
;     ss = wave_sum(ss, lane);
;     const float inv = rsqrtf(ss * (1.f / D_) + EPS_);
;     const u16* xr = p->xb + (size_t)row * D_;
;     float* orow = p->xres + (size_t)row * D_;
; #pragma unroll
;     for (int i = 0; i < 4; ++i) {
;       const int c = (lane + 64 * i) * 8;
;       const bf16x8 v = ld_nt16h(xr + c);
;       const float4 g0 = *(const float4*)(p->final_norm + c), g1 = *(const float4*)(p->final_norm + c + 4);
;       float4 o0, o1;
;       o0.x = bf2f((u16)v[0]) * inv * g0.x; o0.y = bf2f((u16)v[1]) * inv * g0.y;
;       o0.z = bf2f((u16)v[2]) * inv * g0.z; o0.w = bf2f((u16)v[3]) * inv * g0.w;
;       o1.x = bf2f((u16)v[4]) * inv * g1.x; o1.y = bf2f((u16)v[5]) * inv * g1.y;
;       o1.z = bf2f((u16)v[6]) * inv * g1.z; o1.w = bf2f((u16)v[7]) * inv * g1.w;
;       st_nt16f(orow + c, o0); st_nt16f(orow + c + 4, o1);
;     }
;   }
; }
.LBB0_10:
	s_cmp_gt_u32 s98, 15
	s_cbranch_scc1 .LBB0_622
	s_cmp_gt_i32 s98, 14
	s_mov_b64 s[4:5], -1
	s_cbranch_scc0 .LBB0_18
	v_mov_b32_e32 v1, v210
	s_mov_b32 s4, s2
	v_ashrrev_i32_e32 v0, 6, v1
	s_nop 0
	v_lshl_add_u32 v0, s4, 3, v0
	v_cmp_gt_i32_e32 vcc, s71, v0
	s_and_saveexec_b64 s[8:9], vcc
	s_cbranch_execz .LBB0_17
	s_load_dwordx4 s[4:7], s[0:1], 0x78
	s_load_dwordx2 s[10:11], s[0:1], 0xb0
	v_and_b32_e32 v1, 63, v1
	v_lshlrev_b32_e32 v12, 3, v1
	v_lshlrev_b32_e32 v2, 2, v1
	v_lshlrev_b32_e32 v192, 5, v1
	v_or_b32_e32 v14, 0x400, v12
	v_xor_b32_e32 v16, 0x80, v2
	s_waitcnt lgkmcnt(0)
	v_lshl_add_u64 v[2:3], s[4:5], 0, v[192:193]
	v_lshlrev_b32_e32 v192, 2, v14
	v_or_b32_e32 v18, 0x600, v12
	v_lshl_add_u64 v[4:5], s[4:5], 0, v[192:193]
	v_lshlrev_b32_e32 v192, 2, v18
	v_lshlrev_b32_e32 v10, 14, v1
	v_lshl_add_u64 v[6:7], s[4:5], 0, v[192:193]
	v_lshlrev_b32_e32 v192, 4, v1
	v_cmp_lt_u32_e32 vcc, 31, v1
	v_lshl_add_u64 v[8:9], s[10:11], 0, v[192:193]
	s_mov_b64 s[10:11], 0
	v_lshlrev_b32_e32 v192, 2, v10
	v_lshlrev_b32_e32 v10, 2, v12
	v_mov_b32_e32 v11, v193
	v_lshlrev_b32_e32 v12, 2, v14
	v_mov_b32_e32 v13, v193
	v_lshlrev_b32_e32 v14, 2, v18
	v_mov_b32_e32 v15, v193
	s_load_dwordx2 s[12:13], s[0:1], 0xe8
	global_load_dwordx4 v[100:103], v[2:3], off
	global_load_dwordx4 v[104:107], v[2:3], off offset:16
	global_load_dwordx4 v[108:111], v[2:3], off offset:2048
	global_load_dwordx4 v[112:115], v[2:3], off offset:2064
	global_load_dwordx4 v[116:119], v[4:5], off
	global_load_dwordx4 v[120:123], v[4:5], off offset:16
	global_load_dwordx4 v[124:127], v[6:7], off
	global_load_dwordx4 v[128:131], v[6:7], off offset:16
	v_readfirstlane_b32 s14, v0
	s_waitcnt lgkmcnt(0)
	v_lshl_add_u64 v[148:149], s[12:13], 0, v[192:193]
	s_lshl_b32 s16, s14, 2
	s_mov_b32 s17, 0
	v_lshl_add_u64 v[150:151], v[148:149], 0, s[16:17]
	global_load_dword v17, v[150:151], off
	s_lshl_b32 s16, s14, 12
	v_lshl_add_u64 v[150:151], v[8:9], 0, s[16:17]
	global_load_dwordx4 v[18:21], v[150:151], off nt
	global_load_dwordx4 v[44:47], v[150:151], off offset:1024 nt
	global_load_dwordx4 v[48:51], v[150:151], off offset:2048 nt
	global_load_dwordx4 v[52:55], v[150:151], off offset:3072 nt
	s_add_i32 s15, s14, s33
	s_lshl_b32 s16, s15, 2
	s_mov_b32 s17, 0
	v_lshl_add_u64 v[150:151], v[148:149], 0, s[16:17]
	global_load_dword v61, v[150:151], off
	s_lshl_b32 s16, s15, 12
	v_lshl_add_u64 v[150:151], v[8:9], 0, s[16:17]
	global_load_dwordx4 v[132:135], v[150:151], off nt
	global_load_dwordx4 v[136:139], v[150:151], off offset:1024 nt
	global_load_dwordx4 v[140:143], v[150:151], off offset:2048 nt
	global_load_dwordx4 v[144:147], v[150:151], off offset:3072 nt
	s_lshl_b32 s18, s14, 13
	s_add_u32 s18, s6, s18
	s_addc_u32 s19, s7, 0
	s_waitcnt vmcnt(9)
	v_cndmask_b32_e64 v17, v17, 0, vcc
	ds_swizzle_b32 v60, v17 offset:swizzle(SWAP,1)
	s_waitcnt lgkmcnt(0)
	v_add_f32_e32 v17, v17, v60
	ds_swizzle_b32 v60, v17 offset:swizzle(SWAP,2)
	s_waitcnt lgkmcnt(0)
	v_add_f32_e32 v17, v17, v60
	ds_swizzle_b32 v60, v17 offset:swizzle(SWAP,4)
	s_waitcnt lgkmcnt(0)
	v_add_f32_e32 v17, v17, v60
	ds_swizzle_b32 v60, v17 offset:swizzle(SWAP,8)
	s_waitcnt lgkmcnt(0)
	v_add_f32_e32 v17, v17, v60
	ds_swizzle_b32 v60, v17 offset:swizzle(SWAP,16)
	s_waitcnt lgkmcnt(0)
	v_add_f32_e32 v17, v17, v60
	ds_bpermute_b32 v60, v16, v17
	s_waitcnt lgkmcnt(0)
	v_add_f32_e32 v17, v17, v60
	v_fmamk_f32 v17, v17, 0x3a000000, v211
	v_mul_f32_e32 v60, 0x4b800000, v17
	v_cmp_gt_f32_e64 s[4:5], s77, v17
	v_lshl_add_u64 v[34:35], v[10:11], 0, s[18:19]
	v_lshl_add_u64 v[62:63], v[12:13], 0, s[18:19]
	v_cndmask_b32_e64 v17, v17, v60, s[4:5]
	v_rsq_f32_e32 v17, v17
	v_lshl_add_u64 v[64:65], v[14:15], 0, s[18:19]
	v_mul_f32_e32 v60, 0x45800000, v17
	v_cndmask_b32_e64 v36, v17, v60, s[4:5]
	s_waitcnt vmcnt(8)
	v_lshlrev_b32_e32 v38, 16, v18
	v_and_b32_e32 v39, 0xffff0000, v18
	v_lshlrev_b32_e32 v40, 16, v19
	v_and_b32_e32 v41, 0xffff0000, v19
	v_lshlrev_b32_e32 v66, 16, v20
	v_and_b32_e32 v67, 0xffff0000, v20
	v_lshlrev_b32_e32 v42, 16, v21
	v_and_b32_e32 v43, 0xffff0000, v21
	v_pk_mul_f32 v[38:39], v[36:37], v[38:39] op_sel_hi:[0,1]
	v_pk_mul_f32 v[40:41], v[36:37], v[40:41] op_sel_hi:[0,1]
	v_pk_mul_f32 v[66:67], v[36:37], v[66:67] op_sel_hi:[0,1]
	v_pk_mul_f32 v[42:43], v[36:37], v[42:43] op_sel_hi:[0,1]
	v_pk_mul_f32 v[84:85], v[100:101], v[38:39]
	v_pk_mul_f32 v[86:87], v[102:103], v[40:41]
	v_pk_mul_f32 v[88:89], v[104:105], v[66:67]
	v_pk_mul_f32 v[90:91], v[106:107], v[42:43]
	global_store_dwordx4 v[34:35], v[84:87], off nt
	global_store_dwordx4 v[34:35], v[88:91], off offset:16 nt
	s_waitcnt vmcnt(9)
	v_lshlrev_b32_e32 v38, 16, v44
	v_and_b32_e32 v39, 0xffff0000, v44
	v_lshlrev_b32_e32 v40, 16, v45
	v_and_b32_e32 v41, 0xffff0000, v45
	v_lshlrev_b32_e32 v66, 16, v46
	v_and_b32_e32 v67, 0xffff0000, v46
	v_lshlrev_b32_e32 v42, 16, v47
	v_and_b32_e32 v43, 0xffff0000, v47
	v_pk_mul_f32 v[38:39], v[36:37], v[38:39] op_sel_hi:[0,1]
	v_pk_mul_f32 v[40:41], v[36:37], v[40:41] op_sel_hi:[0,1]
	v_pk_mul_f32 v[66:67], v[36:37], v[66:67] op_sel_hi:[0,1]
	v_pk_mul_f32 v[42:43], v[36:37], v[42:43] op_sel_hi:[0,1]
	v_pk_mul_f32 v[92:93], v[108:109], v[38:39]
	v_pk_mul_f32 v[94:95], v[110:111], v[40:41]
	v_pk_mul_f32 v[96:97], v[112:113], v[66:67]
	v_pk_mul_f32 v[98:99], v[114:115], v[42:43]
	global_store_dwordx4 v[34:35], v[92:95], off offset:2048 nt
	global_store_dwordx4 v[34:35], v[96:99], off offset:2064 nt
	s_waitcnt vmcnt(10)
; __device__ __forceinline__ float bf2f(u16 b) { return __uint_as_float(((unsigned)b) << 16); }
; __device__ __forceinline__ float wave_sum(float v, int lane) {
;   v += swz_xor<1>(v); v += swz_xor<2>(v); v += swz_xor<4>(v); v += swz_xor<8>(v); v += swz_xor<16>(v);
;   v += xor32(v, lane);
;   return v;
; }
; __device__ void final_phase(KP p) {
;   const int tid = tid_v();
;   const int wave = tid >> 6, lane = tid & 63;
;   for (int row = bid_s() * 8 + wave; row < S_; row += gridDim.x * 8) {
;     float ss = (lane < 32) ? p->rowss[(size_t)lane * S_ + row] : 0.f;
;     ss = wave_sum(ss, lane);
;     const float inv = rsqrtf(ss * (1.f / D_) + EPS_);
;     const u16* xr = p->xb + (size_t)row * D_;
;     float* orow = p->xres + (size_t)row * D_;
; #pragma unroll
;     for (int i = 0; i < 4; ++i) {
;       const int c = (lane + 64 * i) * 8;
;       const bf16x8 v = ld_nt16h(xr + c);
;       const float4 g0 = *(const float4*)(p->final_norm + c), g1 = *(const float4*)(p->final_norm + c + 4);
;       float4 o0, o1;
;       o0.x = bf2f((u16)v[0]) * inv * g0.x; o0.y = bf2f((u16)v[1]) * inv * g0.y;
;       o0.z = bf2f((u16)v[2]) * inv * g0.z; o0.w = bf2f((u16)v[3]) * inv * g0.w;
;       o1.x = bf2f((u16)v[4]) * inv * g1.x; o1.y = bf2f((u16)v[5]) * inv * g1.y;
;       o1.z = bf2f((u16)v[6]) * inv * g1.z; o1.w = bf2f((u16)v[7]) * inv * g1.w;
;       st_nt16f(orow + c, o0); st_nt16f(orow + c + 4, o1);
;     }
;   }
; }
	v_lshlrev_b32_e32 v38, 16, v48
	v_and_b32_e32 v39, 0xffff0000, v48
	v_lshlrev_b32_e32 v40, 16, v49
	v_and_b32_e32 v41, 0xffff0000, v49
	v_lshlrev_b32_e32 v66, 16, v50
	v_and_b32_e32 v67, 0xffff0000, v50
	v_lshlrev_b32_e32 v42, 16, v51
	v_and_b32_e32 v43, 0xffff0000, v51
	v_pk_mul_f32 v[38:39], v[36:37], v[38:39] op_sel_hi:[0,1]
	v_pk_mul_f32 v[40:41], v[36:37], v[40:41] op_sel_hi:[0,1]
	v_pk_mul_f32 v[66:67], v[36:37], v[66:67] op_sel_hi:[0,1]
	v_pk_mul_f32 v[42:43], v[36:37], v[42:43] op_sel_hi:[0,1]
	v_pk_mul_f32 v[84:85], v[116:117], v[38:39]
	v_pk_mul_f32 v[86:87], v[118:119], v[40:41]
	v_pk_mul_f32 v[88:89], v[120:121], v[66:67]
	v_pk_mul_f32 v[90:91], v[122:123], v[42:43]
	global_store_dwordx4 v[62:63], v[84:87], off nt
	global_store_dwordx4 v[62:63], v[88:91], off offset:16 nt
	s_waitcnt vmcnt(11)
	v_lshlrev_b32_e32 v38, 16, v52
	v_and_b32_e32 v39, 0xffff0000, v52
	v_lshlrev_b32_e32 v40, 16, v53
	v_and_b32_e32 v41, 0xffff0000, v53
	v_lshlrev_b32_e32 v66, 16, v54
	v_and_b32_e32 v67, 0xffff0000, v54
	v_lshlrev_b32_e32 v42, 16, v55
	v_and_b32_e32 v43, 0xffff0000, v55
	v_pk_mul_f32 v[38:39], v[36:37], v[38:39] op_sel_hi:[0,1]
	v_pk_mul_f32 v[40:41], v[36:37], v[40:41] op_sel_hi:[0,1]
	v_pk_mul_f32 v[66:67], v[36:37], v[66:67] op_sel_hi:[0,1]
	v_pk_mul_f32 v[42:43], v[36:37], v[42:43] op_sel_hi:[0,1]
	v_pk_mul_f32 v[92:93], v[124:125], v[38:39]
	v_pk_mul_f32 v[94:95], v[126:127], v[40:41]
	v_pk_mul_f32 v[96:97], v[128:129], v[66:67]
	v_pk_mul_f32 v[98:99], v[130:131], v[42:43]
	global_store_dwordx4 v[64:65], v[92:95], off nt
	global_store_dwordx4 v[64:65], v[96:99], off offset:16 nt
	s_cmp_gt_i32 s15, s79
	s_cbranch_scc1 .LBB0_17
.Lmy_fin_loop:
	s_add_i32 s14, s15, s33
	s_lshl_b32 s16, s14, 2
	s_mov_b32 s17, 0
	v_lshl_add_u64 v[150:151], v[148:149], 0, s[16:17]
	global_load_dword v17, v[150:151], off
	s_lshl_b32 s16, s14, 12
	v_lshl_add_u64 v[150:151], v[8:9], 0, s[16:17]
	global_load_dwordx4 v[18:21], v[150:151], off nt
	global_load_dwordx4 v[44:47], v[150:151], off offset:1024 nt
	global_load_dwordx4 v[48:51], v[150:151], off offset:2048 nt
	global_load_dwordx4 v[52:55], v[150:151], off offset:3072 nt
	s_lshl_b32 s18, s15, 13
	s_add_u32 s18, s6, s18
	s_addc_u32 s19, s7, 0
	s_waitcnt vmcnt(17)
	v_cndmask_b32_e64 v61, v61, 0, vcc
	ds_swizzle_b32 v60, v61 offset:swizzle(SWAP,1)
	s_waitcnt lgkmcnt(0)
	v_add_f32_e32 v61, v61, v60
	ds_swizzle_b32 v60, v61 offset:swizzle(SWAP,2)
	s_waitcnt lgkmcnt(0)
	v_add_f32_e32 v61, v61, v60
	ds_swizzle_b32 v60, v61 offset:swizzle(SWAP,4)
	s_waitcnt lgkmcnt(0)
	v_add_f32_e32 v61, v61, v60
	ds_swizzle_b32 v60, v61 offset:swizzle(SWAP,8)
	s_waitcnt lgkmcnt(0)
	v_add_f32_e32 v61, v61, v60
	ds_swizzle_b32 v60, v61 offset:swizzle(SWAP,16)
	s_waitcnt lgkmcnt(0)
	v_add_f32_e32 v61, v61, v60
	ds_bpermute_b32 v60, v16, v61
	s_waitcnt lgkmcnt(0)
	v_add_f32_e32 v61, v61, v60
	v_fmamk_f32 v61, v61, 0x3a000000, v211
	v_mul_f32_e32 v60, 0x4b800000, v61
	v_cmp_gt_f32_e64 s[4:5], s77, v61
	v_lshl_add_u64 v[34:35], v[10:11], 0, s[18:19]
	v_lshl_add_u64 v[62:63], v[12:13], 0, s[18:19]
	v_cndmask_b32_e64 v61, v61, v60, s[4:5]
	v_rsq_f32_e32 v61, v61
	v_lshl_add_u64 v[64:65], v[14:15], 0, s[18:19]
	v_mul_f32_e32 v60, 0x45800000, v61
	v_cndmask_b32_e64 v36, v61, v60, s[4:5]
	s_waitcnt vmcnt(16)
	v_lshlrev_b32_e32 v38, 16, v132
	v_and_b32_e32 v39, 0xffff0000, v132
	v_lshlrev_b32_e32 v40, 16, v133
	v_and_b32_e32 v41, 0xffff0000, v133
	v_lshlrev_b32_e32 v66, 16, v134
	v_and_b32_e32 v67, 0xffff0000, v134
	v_lshlrev_b32_e32 v42, 16, v135
	v_and_b32_e32 v43, 0xffff0000, v135
	v_pk_mul_f32 v[38:39], v[36:37], v[38:39] op_sel_hi:[0,1]
	v_pk_mul_f32 v[40:41], v[36:37], v[40:41] op_sel_hi:[0,1]
	v_pk_mul_f32 v[66:67], v[36:37], v[66:67] op_sel_hi:[0,1]
	v_pk_mul_f32 v[42:43], v[36:37], v[42:43] op_sel_hi:[0,1]
	v_pk_mul_f32 v[84:85], v[100:101], v[38:39]
	v_pk_mul_f32 v[86:87], v[102:103], v[40:41]
	v_pk_mul_f32 v[88:89], v[104:105], v[66:67]
	v_pk_mul_f32 v[90:91], v[106:107], v[42:43]
	global_store_dwordx4 v[34:35], v[84:87], off nt
	global_store_dwordx4 v[34:35], v[88:91], off offset:16 nt
	s_waitcnt vmcnt(17)
	v_lshlrev_b32_e32 v38, 16, v136
	v_and_b32_e32 v39, 0xffff0000, v136
	v_lshlrev_b32_e32 v40, 16, v137
	v_and_b32_e32 v41, 0xffff0000, v137
	v_lshlrev_b32_e32 v66, 16, v138
	v_and_b32_e32 v67, 0xffff0000, v138
	v_lshlrev_b32_e32 v42, 16, v139
	v_and_b32_e32 v43, 0xffff0000, v139
	v_pk_mul_f32 v[38:39], v[36:37], v[38:39] op_sel_hi:[0,1]
	v_pk_mul_f32 v[40:41], v[36:37], v[40:41] op_sel_hi:[0,1]
	v_pk_mul_f32 v[66:67], v[36:37], v[66:67] op_sel_hi:[0,1]
	v_pk_mul_f32 v[42:43], v[36:37], v[42:43] op_sel_hi:[0,1]
	v_pk_mul_f32 v[92:93], v[108:109], v[38:39]
	v_pk_mul_f32 v[94:95], v[110:111], v[40:41]
	v_pk_mul_f32 v[96:97], v[112:113], v[66:67]
	v_pk_mul_f32 v[98:99], v[114:115], v[42:43]
	global_store_dwordx4 v[34:35], v[92:95], off offset:2048 nt
	global_store_dwordx4 v[34:35], v[96:99], off offset:2064 nt
	s_waitcnt vmcnt(18)
	v_lshlrev_b32_e32 v38, 16, v140
	v_and_b32_e32 v39, 0xffff0000, v140
	v_lshlrev_b32_e32 v40, 16, v141
	v_and_b32_e32 v41, 0xffff0000, v141
	v_lshlrev_b32_e32 v66, 16, v142
	v_and_b32_e32 v67, 0xffff0000, v142
	v_lshlrev_b32_e32 v42, 16, v143
	v_and_b32_e32 v43, 0xffff0000, v143
	v_pk_mul_f32 v[38:39], v[36:37], v[38:39] op_sel_hi:[0,1]
	v_pk_mul_f32 v[40:41], v[36:37], v[40:41] op_sel_hi:[0,1]
	v_pk_mul_f32 v[66:67], v[36:37], v[66:67] op_sel_hi:[0,1]
	v_pk_mul_f32 v[42:43], v[36:37], v[42:43] op_sel_hi:[0,1]
	v_pk_mul_f32 v[84:85], v[116:117], v[38:39]
	v_pk_mul_f32 v[86:87], v[118:119], v[40:41]
	v_pk_mul_f32 v[88:89], v[120:121], v[66:67]
	v_pk_mul_f32 v[90:91], v[122:123], v[42:43]
	global_store_dwordx4 v[62:63], v[84:87], off nt
	global_store_dwordx4 v[62:63], v[88:91], off offset:16 nt
	s_waitcnt vmcnt(19)
	v_lshlrev_b32_e32 v38, 16, v144
	v_and_b32_e32 v39, 0xffff0000, v144
	v_lshlrev_b32_e32 v40, 16, v145
	v_and_b32_e32 v41, 0xffff0000, v145
	v_lshlrev_b32_e32 v66, 16, v146
	v_and_b32_e32 v67, 0xffff0000, v146
	v_lshlrev_b32_e32 v42, 16, v147
	v_and_b32_e32 v43, 0xffff0000, v147
	v_pk_mul_f32 v[38:39], v[36:37], v[38:39] op_sel_hi:[0,1]
	v_pk_mul_f32 v[40:41], v[36:37], v[40:41] op_sel_hi:[0,1]
	v_pk_mul_f32 v[66:67], v[36:37], v[66:67] op_sel_hi:[0,1]
	v_pk_mul_f32 v[42:43], v[36:37], v[42:43] op_sel_hi:[0,1]
	v_pk_mul_f32 v[92:93], v[124:125], v[38:39]
	v_pk_mul_f32 v[94:95], v[126:127], v[40:41]
	v_pk_mul_f32 v[96:97], v[128:129], v[66:67]
	v_pk_mul_f32 v[98:99], v[130:131], v[42:43]
	global_store_dwordx4 v[64:65], v[92:95], off nt
	global_store_dwordx4 v[64:65], v[96:99], off offset:16 nt
	s_cmp_gt_i32 s14, s79
	s_cbranch_scc1 .LBB0_17
; __device__ __forceinline__ float bf2f(u16 b) { return __uint_as_float(((unsigned)b) << 16); }
; __device__ __forceinline__ float wave_sum(float v, int lane) {
;   v += swz_xor<1>(v); v += swz_xor<2>(v); v += swz_xor<4>(v); v += swz_xor<8>(v); v += swz_xor<16>(v);
;   v += xor32(v, lane);
;   return v;
; }
; __device__ void final_phase(KP p) {
;   const int tid = tid_v();
;   const int wave = tid >> 6, lane = tid & 63;
;   for (int row = bid_s() * 8 + wave; row < S_; row += gridDim.x * 8) {
;     float ss = (lane < 32) ? p->rowss[(size_t)lane * S_ + row] : 0.f;
;     ss = wave_sum(ss, lane);
;     const float inv = rsqrtf(ss * (1.f / D_) + EPS_);
;     const u16* xr = p->xb + (size_t)row * D_;
;     float* orow = p->xres + (size_t)row * D_;
; #pragma unroll
;     for (int i = 0; i < 4; ++i) {
;       const int c = (lane + 64 * i) * 8;
;       const bf16x8 v = ld_nt16h(xr + c);
;       const float4 g0 = *(const float4*)(p->final_norm + c), g1 = *(const float4*)(p->final_norm + c + 4);
;       float4 o0, o1;
;       o0.x = bf2f((u16)v[0]) * inv * g0.x; o0.y = bf2f((u16)v[1]) * inv * g0.y;
;       o0.z = bf2f((u16)v[2]) * inv * g0.z; o0.w = bf2f((u16)v[3]) * inv * g0.w;
;       o1.x = bf2f((u16)v[4]) * inv * g1.x; o1.y = bf2f((u16)v[5]) * inv * g1.y;
;       o1.z = bf2f((u16)v[6]) * inv * g1.z; o1.w = bf2f((u16)v[7]) * inv * g1.w;
;       st_nt16f(orow + c, o0); st_nt16f(orow + c + 4, o1);
;     }
;   }
; }
	s_add_i32 s15, s14, s33
	s_lshl_b32 s16, s15, 2
	s_mov_b32 s17, 0
	v_lshl_add_u64 v[150:151], v[148:149], 0, s[16:17]
	global_load_dword v61, v[150:151], off
	s_lshl_b32 s16, s15, 12
	v_lshl_add_u64 v[150:151], v[8:9], 0, s[16:17]
	global_load_dwordx4 v[132:135], v[150:151], off nt
	global_load_dwordx4 v[136:139], v[150:151], off offset:1024 nt
	global_load_dwordx4 v[140:143], v[150:151], off offset:2048 nt
	global_load_dwordx4 v[144:147], v[150:151], off offset:3072 nt
	s_lshl_b32 s18, s14, 13
	s_add_u32 s18, s6, s18
	s_addc_u32 s19, s7, 0
	s_waitcnt vmcnt(17)
	v_cndmask_b32_e64 v17, v17, 0, vcc
	ds_swizzle_b32 v60, v17 offset:swizzle(SWAP,1)
	s_waitcnt lgkmcnt(0)
	v_add_f32_e32 v17, v17, v60
	ds_swizzle_b32 v60, v17 offset:swizzle(SWAP,2)
	s_waitcnt lgkmcnt(0)
	v_add_f32_e32 v17, v17, v60
	ds_swizzle_b32 v60, v17 offset:swizzle(SWAP,4)
	s_waitcnt lgkmcnt(0)
	v_add_f32_e32 v17, v17, v60
	ds_swizzle_b32 v60, v17 offset:swizzle(SWAP,8)
	s_waitcnt lgkmcnt(0)
	v_add_f32_e32 v17, v17, v60
	ds_swizzle_b32 v60, v17 offset:swizzle(SWAP,16)
	s_waitcnt lgkmcnt(0)
	v_add_f32_e32 v17, v17, v60
	ds_bpermute_b32 v60, v16, v17
	s_waitcnt lgkmcnt(0)
	v_add_f32_e32 v17, v17, v60
	v_fmamk_f32 v17, v17, 0x3a000000, v211
	v_mul_f32_e32 v60, 0x4b800000, v17
	v_cmp_gt_f32_e64 s[4:5], s77, v17
	v_lshl_add_u64 v[34:35], v[10:11], 0, s[18:19]
	v_lshl_add_u64 v[62:63], v[12:13], 0, s[18:19]
	v_cndmask_b32_e64 v17, v17, v60, s[4:5]
	v_rsq_f32_e32 v17, v17
	v_lshl_add_u64 v[64:65], v[14:15], 0, s[18:19]
	v_mul_f32_e32 v60, 0x45800000, v17
	v_cndmask_b32_e64 v36, v17, v60, s[4:5]
	s_waitcnt vmcnt(16)
	v_lshlrev_b32_e32 v38, 16, v18
	v_and_b32_e32 v39, 0xffff0000, v18
	v_lshlrev_b32_e32 v40, 16, v19
	v_and_b32_e32 v41, 0xffff0000, v19
	v_lshlrev_b32_e32 v66, 16, v20
	v_and_b32_e32 v67, 0xffff0000, v20
	v_lshlrev_b32_e32 v42, 16, v21
	v_and_b32_e32 v43, 0xffff0000, v21
	v_pk_mul_f32 v[38:39], v[36:37], v[38:39] op_sel_hi:[0,1]
	v_pk_mul_f32 v[40:41], v[36:37], v[40:41] op_sel_hi:[0,1]
	v_pk_mul_f32 v[66:67], v[36:37], v[66:67] op_sel_hi:[0,1]
	v_pk_mul_f32 v[42:43], v[36:37], v[42:43] op_sel_hi:[0,1]
	v_pk_mul_f32 v[84:85], v[100:101], v[38:39]
	v_pk_mul_f32 v[86:87], v[102:103], v[40:41]
	v_pk_mul_f32 v[88:89], v[104:105], v[66:67]
	v_pk_mul_f32 v[90:91], v[106:107], v[42:43]
	global_store_dwordx4 v[34:35], v[84:87], off nt
	global_store_dwordx4 v[34:35], v[88:91], off offset:16 nt
	s_waitcnt vmcnt(17)
	v_lshlrev_b32_e32 v38, 16, v44
	v_and_b32_e32 v39, 0xffff0000, v44
	v_lshlrev_b32_e32 v40, 16, v45
	v_and_b32_e32 v41, 0xffff0000, v45
	v_lshlrev_b32_e32 v66, 16, v46
	v_and_b32_e32 v67, 0xffff0000, v46
	v_lshlrev_b32_e32 v42, 16, v47
	v_and_b32_e32 v43, 0xffff0000, v47
	v_pk_mul_f32 v[38:39], v[36:37], v[38:39] op_sel_hi:[0,1]
	v_pk_mul_f32 v[40:41], v[36:37], v[40:41] op_sel_hi:[0,1]
	v_pk_mul_f32 v[66:67], v[36:37], v[66:67] op_sel_hi:[0,1]
	v_pk_mul_f32 v[42:43], v[36:37], v[42:43] op_sel_hi:[0,1]
	v_pk_mul_f32 v[92:93], v[108:109], v[38:39]
	v_pk_mul_f32 v[94:95], v[110:111], v[40:41]
	v_pk_mul_f32 v[96:97], v[112:113], v[66:67]
	v_pk_mul_f32 v[98:99], v[114:115], v[42:43]
	global_store_dwordx4 v[34:35], v[92:95], off offset:2048 nt
	global_store_dwordx4 v[34:35], v[96:99], off offset:2064 nt
	s_waitcnt vmcnt(18)
	v_lshlrev_b32_e32 v38, 16, v48
	v_and_b32_e32 v39, 0xffff0000, v48
	v_lshlrev_b32_e32 v40, 16, v49
	v_and_b32_e32 v41, 0xffff0000, v49
	v_lshlrev_b32_e32 v66, 16, v50
	v_and_b32_e32 v67, 0xffff0000, v50
	v_lshlrev_b32_e32 v42, 16, v51
	v_and_b32_e32 v43, 0xffff0000, v51
	v_pk_mul_f32 v[38:39], v[36:37], v[38:39] op_sel_hi:[0,1]
	v_pk_mul_f32 v[40:41], v[36:37], v[40:41] op_sel_hi:[0,1]
	v_pk_mul_f32 v[66:67], v[36:37], v[66:67] op_sel_hi:[0,1]
	v_pk_mul_f32 v[42:43], v[36:37], v[42:43] op_sel_hi:[0,1]
	v_pk_mul_f32 v[84:85], v[116:117], v[38:39]
	v_pk_mul_f32 v[86:87], v[118:119], v[40:41]
	v_pk_mul_f32 v[88:89], v[120:121], v[66:67]
	v_pk_mul_f32 v[90:91], v[122:123], v[42:43]
	global_store_dwordx4 v[62:63], v[84:87], off nt
	global_store_dwordx4 v[62:63], v[88:91], off offset:16 nt
	s_waitcnt vmcnt(19)
	v_lshlrev_b32_e32 v38, 16, v52
	v_and_b32_e32 v39, 0xffff0000, v52
	v_lshlrev_b32_e32 v40, 16, v53
	v_and_b32_e32 v41, 0xffff0000, v53
	v_lshlrev_b32_e32 v66, 16, v54
	v_and_b32_e32 v67, 0xffff0000, v54
	v_lshlrev_b32_e32 v42, 16, v55
	v_and_b32_e32 v43, 0xffff0000, v55
	v_pk_mul_f32 v[38:39], v[36:37], v[38:39] op_sel_hi:[0,1]
	v_pk_mul_f32 v[40:41], v[36:37], v[40:41] op_sel_hi:[0,1]
	v_pk_mul_f32 v[66:67], v[36:37], v[66:67] op_sel_hi:[0,1]
	v_pk_mul_f32 v[42:43], v[36:37], v[42:43] op_sel_hi:[0,1]
	v_pk_mul_f32 v[92:93], v[124:125], v[38:39]
	v_pk_mul_f32 v[94:95], v[126:127], v[40:41]
	v_pk_mul_f32 v[96:97], v[128:129], v[66:67]
	v_pk_mul_f32 v[98:99], v[130:131], v[42:43]
	global_store_dwordx4 v[64:65], v[92:95], off nt
	global_store_dwordx4 v[64:65], v[96:99], off offset:16 nt
	s_cmp_gt_i32 s15, s79
	s_cbranch_scc0 .Lmy_fin_loop
